# sc1 write-through on in-proj and up-proj output stores (repeat)
# speedup vs baseline: 1.0025x; 1.0025x over previous
; __device__ __forceinline__ u32x4 pack8(const f32x4 v0, const f32x4 v1) { u32x4 w; w.x = cvt_pk_bf16(v0[0], v0[1]); w.y = cvt_pk_bf16(v0[2], v0[3]); w.z = cvt_pk_bf16(v1[0], v1[1]); w.w = cvt_pk_bf16(v1[2], v1[3]); return w; }
;     __device__ __forceinline__ void operator()(const f32x4 (&acc)[2][2][4][2], const Unit& u, int wr, int wc, int fr, int fq) const {
;         int colt = u.pn * BM; bf16_t* base = O; int ldc = ld;
;         if (colt >= split_col) { base = O2; ldc = ld2; colt -= split_col; }
;         const unsigned loff = (unsigned)((PERMROW ? 4 * fr : fr) * ldc + 8 * fq) * 2u;
;         char* ub = (char*)base + ((size_t)(u.pm * BM + wr * 64) * ldc + (size_t)(colt + wc * 32)) * 2;
; #pragma unroll
;         for (int ai = 0; ai < 2; ++ai)
; #pragma unroll
;             for (int m = 0; m < 4; ++m) {
; #pragma unroll
;                 for (int bj = 0; bj < 2; ++bj) *(u32x4*)(ub + ((size_t)(ai * HALF + (PERMROW ? m : m * 16)) * ldc + bj * HALF) * 2 + loff) = pack8(acc[ai][bj][m][0], acc[ai][bj][m][1]); }
;     }
.LBB0_133:
	s_lshl_b32 s7, s31, 8
	s_cmp_lt_i32 s31, 24
	s_cselect_b32 s9, 0, 0xffffe800
	s_cselect_b32 s16, s83, s61
	s_cselect_b32 s17, s82, s60
	s_cselect_b32 s18, 0x1800, s41
	s_lshl_b32 s14, s30, 8
	s_or_b32 s7, s7, s28
	s_add_i32 s14, s14, s27
	s_add_i32 s7, s7, s9
	s_mul_hi_i32 s15, s14, s18
	s_mul_i32 s14, s14, s18
	s_ashr_i32 s9, s7, 31
	s_add_u32 s14, s14, s7
	s_addc_u32 s15, s15, s9
	s_lshl_b64 s[14:15], s[14:15], 1
	v_mul_u32_u24_e32 v144, s18, v142
	s_add_u32 s14, s17, s14
	v_or_b32_e32 v144, v144, v140
	s_addc_u32 s15, s16, s15
	v_mov_b32_e32 v145, v192
	v_readlane_b32 s16, v254, 58
	v_lshl_add_u64 v[146:147], s[14:15], 0, v[144:145]
	v_readlane_b32 s17, v254, 59
	s_lshl_b32 s16, s18, 5
	v_cvt_pk_bf16_f32 v112, v112, v113
	v_cvt_pk_bf16_f32 v113, v114, v115
	v_cvt_pk_bf16_f32 v115, v106, v107
	v_cvt_pk_bf16_f32 v106, v108, v109
	s_nop 0
	v_lshl_add_u64 v[108:109], v[146:147], 0, s[16:17]
	v_cvt_pk_bf16_f32 v96, v96, v97
	v_cvt_pk_bf16_f32 v97, v98, v99
	v_cvt_pk_bf16_f32 v99, v90, v91
	v_cvt_pk_bf16_f32 v90, v92, v93
	v_lshl_add_u64 v[92:93], v[108:109], 0, s[16:17]
	v_cvt_pk_bf16_f32 v124, v124, v125
	v_cvt_pk_bf16_f32 v125, v126, v127
	v_cvt_pk_bf16_f32 v126, v120, v121
	v_cvt_pk_bf16_f32 v127, v122, v123
	global_store_dwordx4 v144, v[124:127], s[14:15] sc1
	v_cvt_pk_bf16_f32 v114, v104, v105
	global_store_dwordx4 v144, v[112:115], s[14:15] offset:256 sc1
	v_cvt_pk_bf16_f32 v80, v80, v81
	v_cvt_pk_bf16_f32 v81, v82, v83
	v_cvt_pk_bf16_f32 v83, v74, v75
	v_cvt_pk_bf16_f32 v74, v76, v77
	v_lshl_add_u64 v[76:77], v[92:93], 0, s[16:17]
	s_mul_i32 s14, s18, 0xa0
	s_mov_b32 s15, s17
	v_cvt_pk_bf16_f32 v60, v60, v61
	v_cvt_pk_bf16_f32 v61, v62, v63
	v_cvt_pk_bf16_f32 v62, v56, v57
	v_lshl_add_u64 v[56:57], v[76:77], 0, s[14:15]
	v_cvt_pk_bf16_f32 v48, v48, v49
	v_cvt_pk_bf16_f32 v49, v50, v51
	v_cvt_pk_bf16_f32 v51, v42, v43
	v_cvt_pk_bf16_f32 v42, v44, v45
	v_lshl_add_u64 v[44:45], v[56:57], 0, s[16:17]
	s_mov_b32 s7, s17
	v_cvt_pk_bf16_f32 v32, v32, v33
	v_cvt_pk_bf16_f32 v33, v34, v35
	v_cvt_pk_bf16_f32 v35, v26, v27
	v_cvt_pk_bf16_f32 v26, v28, v29
	v_lshl_add_u64 v[28:29], v[44:45], 0, s[16:17]
	v_writelane_b32 v254, s6, 58
	v_cvt_pk_bf16_f32 v16, v16, v17
	v_cvt_pk_bf16_f32 v17, v18, v19
	v_cvt_pk_bf16_f32 v19, v10, v11
	v_cvt_pk_bf16_f32 v10, v12, v13
	v_lshl_add_u64 v[12:13], v[28:29], 0, s[16:17]
	s_nop 0
	v_writelane_b32 v254, s7, 59
	s_andn2_b64 vcc, exec, s[0:1]
	s_mov_b64 s[0:1], -1
	v_cvt_pk_bf16_f32 v104, v116, v117
	v_cvt_pk_bf16_f32 v105, v118, v119
	v_cvt_pk_bf16_f32 v107, v110, v111
	global_store_dwordx4 v[108:109], v[104:107], off sc1
	v_cvt_pk_bf16_f32 v98, v88, v89
	global_store_dwordx4 v[108:109], v[96:99], off offset:256 sc1
	v_cvt_pk_bf16_f32 v88, v100, v101
	v_cvt_pk_bf16_f32 v89, v102, v103
	v_cvt_pk_bf16_f32 v91, v94, v95
	global_store_dwordx4 v[92:93], v[88:91], off sc1
	v_cvt_pk_bf16_f32 v82, v72, v73
	global_store_dwordx4 v[92:93], v[80:83], off offset:256 sc1
	v_cvt_pk_bf16_f32 v72, v84, v85
	v_cvt_pk_bf16_f32 v73, v86, v87
	v_cvt_pk_bf16_f32 v75, v78, v79
	global_store_dwordx4 v[76:77], v[72:75], off sc1
	v_cvt_pk_bf16_f32 v68, v68, v69
	v_cvt_pk_bf16_f32 v69, v70, v71
	v_cvt_pk_bf16_f32 v70, v64, v65
	v_cvt_pk_bf16_f32 v71, v66, v67
	global_store_dwordx4 v[76:77], v[68:71], off offset:256 sc1
	v_cvt_pk_bf16_f32 v63, v58, v59
	global_store_dwordx4 v[56:57], v[60:63], off sc1
	v_cvt_pk_bf16_f32 v50, v40, v41
	global_store_dwordx4 v[56:57], v[48:51], off offset:256 sc1
	v_cvt_pk_bf16_f32 v40, v52, v53
	v_cvt_pk_bf16_f32 v41, v54, v55
	v_cvt_pk_bf16_f32 v43, v46, v47
	global_store_dwordx4 v[44:45], v[40:43], off sc1
	v_cvt_pk_bf16_f32 v34, v24, v25
	global_store_dwordx4 v[44:45], v[32:35], off offset:256 sc1
	v_cvt_pk_bf16_f32 v24, v36, v37
	v_cvt_pk_bf16_f32 v25, v38, v39
	v_cvt_pk_bf16_f32 v27, v30, v31
	global_store_dwordx4 v[28:29], v[24:27], off sc1
	v_cvt_pk_bf16_f32 v18, v8, v9
	global_store_dwordx4 v[28:29], v[16:19], off offset:256 sc1
	v_cvt_pk_bf16_f32 v8, v20, v21
	v_cvt_pk_bf16_f32 v9, v22, v23
	v_cvt_pk_bf16_f32 v11, v14, v15
	global_store_dwordx4 v[12:13], v[8:11], off sc1
	v_cvt_pk_bf16_f32 v4, v4, v5
	v_cvt_pk_bf16_f32 v5, v6, v7
	v_cvt_pk_bf16_f32 v6, v0, v1
	v_cvt_pk_bf16_f32 v7, v2, v3
	global_store_dwordx4 v[12:13], v[4:7], off offset:256 sc1
	s_cbranch_vccnz .LBB0_126
	s_andn2_b64 vcc, exec, s[2:3]
	s_cbranch_vccnz .LBB0_125
	s_barrier
	s_branch .LBB0_125

;     __device__ __forceinline__ void operator()(const f32x4 (&acc)[2][2][4][2], const Unit& u, int wr, int wc, int fr, int fq) const {
;     ...
;           if (wr == 0 && fr == 0) { float* tp = TOP + ((size_t)u.pm * 2) * (2 * DFF) + u.pn * BM + colb;
; #pragma unroll
;               for (int bj = 0; bj < 2; ++bj)
; #pragma unroll
;                   for (int n = 0; n < 2; ++n) { *(f32x4*)(tp + bj * HALF + 4 * n) = acc[0][bj][0][n]; *(f32x4*)(tp + (2 * DFF) + bj * HALF + 4 * n) = acc[0][bj][1][n]; } }
;           if (wr == 1 && fr == 15) { float* bp = BOT + ((size_t)u.pm * 2) * (2 * DFF) + u.pn * BM + colb;
; #pragma unroll
;               for (int bj = 0; bj < 2; ++bj)
; #pragma unroll
;                   for (int n = 0; n < 2; ++n) { *(f32x4*)(bp + bj * HALF + 4 * n) = acc[1][bj][2][n]; *(f32x4*)(bp + (2 * DFF) + bj * HALF + 4 * n) = acc[1][bj][3][n]; } } }
;     ...
;             for (int n = 0; n < 2; ++n) {
;                 const f32x4 wg0 = wgt[n][0], wg1 = wgt[n][1], wg2 = wgt[n][2], bg = wgt[n][3], wv0 = wgt[n][4], wv1 = wgt[n][5], wv2 = wgt[n][6], bv = wgt[n][7];
; #pragma unroll
;                 for (int jp = 0; jp < 2; ++jp) {
;                     const int ja = 2 * jp, jb = 2 * jp + 1;
;                     const int vga = ((0 * 2 + n) * 4 + ja) * 2, vgb = ((0 * 2 + n) * 4 + jb) * 2, vva = ((1 * 2 + n) * 4 + ja) * 2, vvb = ((1 * 2 + n) * 4 + jb) * 2;
;                     const float hg2a = hl[vga * 4], hg1a = hl[(vga + 1) * 4], hg2b = hl[vgb * 4], hg1b = hl[(vgb + 1) * 4];
;                     const float hv2a = hl[vva * 4], hv1a = hl[(vva + 1) * 4], hv2b = hl[vvb * 4], hv1b = hl[(vvb + 1) * 4];
;     ...
;                     const f32x2 g0 = UC_PAIR(0, 0), g1 = UC_PAIR(0, 1), g2 = UC_PAIR(0, 2), g3 = UC_PAIR(0, 3);
;                     const f32x2 v0 = UC_PAIR(1, 0), v1 = UC_PAIR(1, 1), v2 = UC_PAIR(1, 2), v3 = UC_PAIR(1, 3);
;     ...
;                     f32x2 gp1, gp2, vp1, vp2;
;                     gp1.x = dpp_shr1_keep(hg1a, g3.x); gp1.y = dpp_shr1_keep(hg1b, g3.y); gp2.x = dpp_shr1_keep(hg2a, g2.x); gp2.y = dpp_shr1_keep(hg2b, g2.y);
;                     vp1.x = dpp_shr1_keep(hv1a, v3.x); vp1.y = dpp_shr1_keep(hv1b, v3.y); vp2.x = dpp_shr1_keep(hv2a, v2.x); vp2.y = dpp_shr1_keep(hv2b, v2.y);
;                     const f32x2 a0 = jp == 0 ? lo2(wg0) : hi2(wg0), a1 = jp == 0 ? lo2(wg1) : hi2(wg1), a2 = jp == 0 ? lo2(wg2) : hi2(wg2), ab = jp == 0 ? lo2(bg) : hi2(bg);
.LBB0_533:
	s_or_b64 exec, exec, s[20:21]
	s_mul_hi_i32 s13, s33, 0x16000
	s_mul_i32 s15, s33, 0x16000
	v_lshlrev_b32_e32 v246, 2, v214
	s_and_saveexec_b64 s[20:21], s[42:43]
	s_cbranch_execz .LBB0_535
	v_readlane_b32 s22, v253, 11
	v_readlane_b32 s23, v253, 12
	s_add_u32 s24, s22, s15
	s_addc_u32 s25, s23, s13
	s_lshl_b32 s22, s38, 8
	s_ashr_i32 s23, s22, 31
	s_lshl_b64 s[22:23], s[22:23], 2
	s_add_u32 s22, s24, s22
	s_addc_u32 s23, s25, s23
	v_mov_b32_e32 v247, v192
	v_lshl_add_u64 v[248:249], s[22:23], 0, v[246:247]
	v_add_co_u32_e32 v248, vcc, 0xb000, v248
	global_store_dwordx4 v246, v[184:187], s[22:23] sc1
	s_nop 0
	v_addc_co_u32_e32 v249, vcc, 0, v249, vcc
	global_store_dwordx4 v[248:249], v[180:183], off sc1
	global_store_dwordx4 v246, v[92:95], s[22:23] offset:16 sc1
	global_store_dwordx4 v[248:249], v[88:91], off offset:16 sc1
	global_store_dwordx4 v246, v[164:167], s[22:23] offset:512 sc1
	global_store_dwordx4 v[248:249], v[156:159], off offset:512 sc1
	global_store_dwordx4 v246, v[76:79], s[22:23] offset:528 sc1
	global_store_dwordx4 v[248:249], v[72:75], off offset:528 sc1
.LBB0_535:
	s_or_b64 exec, exec, s[20:21]
	s_and_saveexec_b64 s[20:21], s[8:9]
	s_cbranch_execz .LBB0_537
	v_readlane_b32 s22, v253, 13
	v_readlane_b32 s23, v253, 14
	s_add_u32 s15, s22, s15
	s_addc_u32 s13, s23, s13
	s_lshl_b32 s22, s38, 8
	s_ashr_i32 s23, s22, 31
	s_lshl_b64 s[22:23], s[22:23], 2
	s_add_u32 s22, s15, s22
	s_addc_u32 s23, s13, s23
	v_mov_b32_e32 v247, v192
	v_lshl_add_u64 v[248:249], s[22:23], 0, v[246:247]
	v_add_co_u32_e32 v248, vcc, 0xb000, v248
	global_store_dwordx4 v246, v[52:55], s[22:23] sc1
	s_nop 0
	v_addc_co_u32_e32 v249, vcc, 0, v249, vcc
	global_store_dwordx4 v[248:249], v[48:51], off sc1
	global_store_dwordx4 v246, v[20:23], s[22:23] offset:16 sc1
	global_store_dwordx4 v[248:249], v[16:19], off offset:16 sc1
	global_store_dwordx4 v246, v[36:39], s[22:23] offset:512 sc1
	global_store_dwordx4 v[248:249], v[32:35], off offset:512 sc1
	global_store_dwordx4 v246, v[4:7], s[22:23] offset:528 sc1
	global_store_dwordx4 v[248:249], v[0:3], off offset:528 sc1
.LBB0_537:
	s_or_b64 exec, exec, s[20:21]
	s_waitcnt lgkmcnt(0)
	s_barrier
	s_mov_b32 s21, 0
	s_mov_b32 s20, 0x40135761
	ds_read2_b32 v[228:229], v223 offset1:4
	ds_read2_b32 v[238:239], v223 offset0:8 offset1:12
	ds_read2_b32 v[240:241], v223 offset0:64 offset1:68
	ds_read2_b32 v[242:243], v223 offset0:72 offset1:76
	v_lshl_add_u32 v226, s33, 8, v215
	s_waitcnt lgkmcnt(0)
	v_mov_b32_dpp v229, v172 row_shr:1 row_mask:0xf bank_mask:0xf
	v_mov_b32_dpp v238, v177 row_shr:1 row_mask:0xf bank_mask:0xf
	v_mov_b32_dpp v239, v173 row_shr:1 row_mask:0xf bank_mask:0xf
	v_mov_b32_e32 v244, v229
	v_mov_b32_dpp v228, v176 row_shr:1 row_mask:0xf bank_mask:0xf
	v_mov_b32_e32 v229, v238
	v_mov_b32_e32 v245, v239
	v_mov_b32_dpp v241, v140 row_shr:1 row_mask:0xf bank_mask:0xf
	v_mov_b32_dpp v243, v141 row_shr:1 row_mask:0xf bank_mask:0xf
	v_mov_b32_dpp v242, v149 row_shr:1 row_mask:0xf bank_mask:0xf
	v_mov_b32_e32 v238, v241
	v_mov_b32_e32 v239, v243
	v_mov_b32_e32 v241, v242
	v_mov_b32_dpp v240, v148 row_shr:1 row_mask:0xf bank_mask:0xf
	s_waitcnt vmcnt(0)
	v_pk_fma_f32 v[228:229], v[128:129], v[228:229], v[144:145]
	s_nop 0
	v_pk_fma_f32 v[228:229], v[132:133], v[244:245], v[228:229]
	v_pk_fma_f32 v[242:243], v[128:129], v[244:245], v[144:145]
	v_pk_fma_f32 v[228:229], v[184:185], v[136:137], v[228:229]
	v_pk_fma_f32 v[242:243], v[184:185], v[132:133], v[242:243]
	v_pk_fma_f32 v[184:185], v[184:185], v[128:129], v[144:145]
	v_pk_fma_f32 v[242:243], v[180:181], v[136:137], v[242:243]
	v_pk_fma_f32 v[184:185], v[180:181], v[132:133], v[184:185]
	v_pk_fma_f32 v[180:181], v[180:181], v[128:129], v[144:145]
	v_pk_fma_f32 v[184:185], v[176:177], v[136:137], v[184:185]
	v_pk_fma_f32 v[176:177], v[176:177], v[132:133], v[180:181]
	v_pk_mul_f32 v[180:181], v[184:185], v[184:185]
	v_pk_fma_f32 v[176:177], v[172:173], v[136:137], v[176:177]
	v_mov_b64_e32 v[172:173], s[20:21]
	s_mov_b32 s20, 0x3dd2d3e7
	v_pk_fma_f32 v[180:181], v[180:181], s[20:21], v[172:173] op_sel_hi:[1,0,0]
	v_pk_fma_f32 v[240:241], v[160:161], v[240:241], v[188:189]
	v_pk_mul_f32 v[180:181], v[184:185], v[180:181]
	v_pk_fma_f32 v[240:241], v[168:169], v[238:239], v[240:241]
	v_exp_f32_e32 v180, v180
	v_exp_f32_e32 v181, v181
	v_pk_fma_f32 v[238:239], v[160:161], v[238:239], v[188:189]
	v_pk_fma_f32 v[240:241], v[164:165], v[152:153], v[240:241]
	v_pk_fma_f32 v[238:239], v[164:165], v[168:169], v[238:239]
	v_pk_add_f32 v[180:181], v[180:181], 1.0 op_sel_hi:[1,0]
	v_pk_fma_f32 v[164:165], v[164:165], v[160:161], v[188:189]
	v_rcp_f32_e32 v180, v180
	v_rcp_f32_e32 v181, v181
	v_pk_fma_f32 v[238:239], v[156:157], v[152:153], v[238:239]
	v_pk_fma_f32 v[164:165], v[156:157], v[168:169], v[164:165]
	v_pk_fma_f32 v[156:157], v[156:157], v[160:161], v[188:189]
	v_pk_fma_f32 v[164:165], v[148:149], v[152:153], v[164:165]
	v_pk_fma_f32 v[148:149], v[148:149], v[168:169], v[156:157]
	v_pk_fma_f32 v[180:181], v[184:185], v[180:181], v[184:185] neg_lo:[1,0,0] neg_hi:[1,0,0]
	v_pk_fma_f32 v[140:141], v[140:141], v[152:153], v[148:149]
	v_pk_mul_f32 v[148:149], v[228:229], v[228:229]
	v_pk_mul_f32 v[180:181], v[164:165], v[180:181]
	v_pk_fma_f32 v[148:149], v[148:149], s[20:21], v[172:173] op_sel_hi:[1,0,0]
	v_pk_mul_f32 v[164:165], v[176:177], v[176:177]
	v_pk_mul_f32 v[148:149], v[228:229], v[148:149]
	v_pk_fma_f32 v[164:165], v[164:165], s[20:21], v[172:173] op_sel_hi:[1,0,0]
	v_exp_f32_e32 v148, v148
	v_exp_f32_e32 v149, v149
	v_pk_mul_f32 v[164:165], v[176:177], v[164:165]
	v_pk_mul_f32 v[156:157], v[242:243], v[242:243]
	v_exp_f32_e32 v164, v164
	v_exp_f32_e32 v165, v165
	v_pk_add_f32 v[148:149], v[148:149], 1.0 op_sel_hi:[1,0]
	v_pk_fma_f32 v[156:157], v[156:157], s[20:21], v[172:173] op_sel_hi:[1,0,0]
	v_rcp_f32_e32 v148, v148
	v_rcp_f32_e32 v149, v149
	v_pk_add_f32 v[164:165], v[164:165], 1.0 op_sel_hi:[1,0]
	v_pk_mul_f32 v[156:157], v[242:243], v[156:157]
	v_rcp_f32_e32 v164, v164
	v_rcp_f32_e32 v165, v165
	v_exp_f32_e32 v156, v156
	v_exp_f32_e32 v157, v157
	v_pk_fma_f32 v[148:149], v[228:229], v[148:149], v[228:229] neg_lo:[1,0,0] neg_hi:[1,0,0]
	v_pk_fma_f32 v[164:165], v[176:177], v[164:165], v[176:177] neg_lo:[1,0,0] neg_hi:[1,0,0]
	v_pk_mul_f32 v[148:149], v[240:241], v[148:149]
	v_pk_add_f32 v[156:157], v[156:157], 1.0 op_sel_hi:[1,0]
	v_pk_mul_f32 v[140:141], v[140:141], v[164:165]
	v_cvt_pk_bf16_f32 v164, v148, v149
	v_cvt_pk_bf16_f32 v148, v180, v181
	ds_read2_b32 v[176:177], v223 offset0:16 offset1:20
	ds_read2_b32 v[180:181], v223 offset0:24 offset1:28
	ds_read2_b32 v[184:185], v223 offset0:80 offset1:84
	ds_read2_b32 v[228:229], v223 offset0:88 offset1:92
	v_rcp_f32_e32 v156, v156
	v_rcp_f32_e32 v157, v157
	s_waitcnt lgkmcnt(3)
;     __device__ __forceinline__ void operator()(const f32x4 (&acc)[2][2][4][2], const Unit& u, int wr, int wc, int fr, int fq) const {
;     ...
;             for (int n = 0; n < 2; ++n) {
;                 const f32x4 wg0 = wgt[n][0], wg1 = wgt[n][1], wg2 = wgt[n][2], bg = wgt[n][3], wv0 = wgt[n][4], wv1 = wgt[n][5], wv2 = wgt[n][6], bv = wgt[n][7];
; #pragma unroll
;                 for (int jp = 0; jp < 2; ++jp) {
;                     const int ja = 2 * jp, jb = 2 * jp + 1;
;                     const int vga = ((0 * 2 + n) * 4 + ja) * 2, vgb = ((0 * 2 + n) * 4 + jb) * 2, vva = ((1 * 2 + n) * 4 + ja) * 2, vvb = ((1 * 2 + n) * 4 + jb) * 2;
;                     const float hg2a = hl[vga * 4], hg1a = hl[(vga + 1) * 4], hg2b = hl[vgb * 4], hg1b = hl[(vgb + 1) * 4];
;                     const float hv2a = hl[vva * 4], hv1a = hl[(vva + 1) * 4], hv2b = hl[vvb * 4], hv1b = hl[(vvb + 1) * 4];
;     ...
;                     const f32x2 g0 = UC_PAIR(0, 0), g1 = UC_PAIR(0, 1), g2 = UC_PAIR(0, 2), g3 = UC_PAIR(0, 3);
;                     const f32x2 v0 = UC_PAIR(1, 0), v1 = UC_PAIR(1, 1), v2 = UC_PAIR(1, 2), v3 = UC_PAIR(1, 3);
;     ...
;                     f32x2 gp1, gp2, vp1, vp2;
;                     gp1.x = dpp_shr1_keep(hg1a, g3.x); gp1.y = dpp_shr1_keep(hg1b, g3.y); gp2.x = dpp_shr1_keep(hg2a, g2.x); gp2.y = dpp_shr1_keep(hg2b, g2.y);
;                     vp1.x = dpp_shr1_keep(hv1a, v3.x); vp1.y = dpp_shr1_keep(hv1b, v3.y); vp2.x = dpp_shr1_keep(hv2a, v2.x); vp2.y = dpp_shr1_keep(hv2b, v2.y);
;                     const f32x2 a0 = jp == 0 ? lo2(wg0) : hi2(wg0), a1 = jp == 0 ? lo2(wg1) : hi2(wg1), a2 = jp == 0 ? lo2(wg2) : hi2(wg2), ab = jp == 0 ? lo2(bg) : hi2(bg);
;                     const f32x2 c0 = jp == 0 ? lo2(wv0) : hi2(wv0), c1 = jp == 0 ? lo2(wv1) : hi2(wv1), c2 = jp == 0 ? lo2(wv2) : hi2(wv2), cb_ = jp == 0 ? lo2(bv) : hi2(bv);
;                     const f32x2 yg0 = ab + a0 * gp2 + a1 * gp1 + a2 * g0, yv0 = cb_ + c0 * vp2 + c1 * vp1 + c2 * v0;
;                     const f32x2 yg1 = ab + a0 * gp1 + a1 * g0 + a2 * g1, yv1 = cb_ + c0 * vp1 + c1 * v0 + c2 * v1;
;                     const f32x2 yg2 = ab + a0 * g0 + a1 * g1 + a2 * g2, yv2 = cb_ + c0 * v0 + c1 * v1 + c2 * v2;
;                     const f32x2 yg3 = ab + a0 * g1 + a1 * g2 + a2 * g3, yv3 = cb_ + c0 * v1 + c1 * v2 + c2 * v3;
	v_mov_b32_dpp v177, v174 row_shr:1 row_mask:0xf bank_mask:0xf
	s_waitcnt lgkmcnt(2)
	v_mov_b32_dpp v180, v179 row_shr:1 row_mask:0xf bank_mask:0xf
	s_waitcnt lgkmcnt(1)
	v_mov_b32_dpp v185, v142 row_shr:1 row_mask:0xf bank_mask:0xf
	v_pk_fma_f32 v[156:157], v[242:243], v[156:157], v[242:243] neg_lo:[1,0,0] neg_hi:[1,0,0]
	s_waitcnt lgkmcnt(0)
	v_mov_b32_dpp v228, v151 row_shr:1 row_mask:0xf bank_mask:0xf
	v_pk_mul_f32 v[156:157], v[238:239], v[156:157]
	v_mov_b32_dpp v181, v175 row_shr:1 row_mask:0xf bank_mask:0xf
	v_mov_b32_e32 v238, v177
	v_mov_b32_e32 v177, v180
	v_mov_b32_dpp v229, v143 row_shr:1 row_mask:0xf bank_mask:0xf
	v_mov_b32_e32 v180, v185
	v_mov_b32_dpp v184, v150 row_shr:1 row_mask:0xf bank_mask:0xf
	v_mov_b32_e32 v185, v228
	v_mov_b32_e32 v239, v181
	v_mov_b32_e32 v181, v229
	v_pk_fma_f32 v[184:185], v[162:163], v[184:185], v[190:191]
	v_mov_b32_dpp v176, v178 row_shr:1 row_mask:0xf bank_mask:0xf
	v_pk_fma_f32 v[184:185], v[170:171], v[180:181], v[184:185]
	v_pk_fma_f32 v[180:181], v[162:163], v[180:181], v[190:191]
	v_pk_fma_f32 v[176:177], v[130:131], v[176:177], v[146:147]
	v_pk_fma_f32 v[184:185], v[166:167], v[154:155], v[184:185]
	v_pk_fma_f32 v[180:181], v[166:167], v[170:171], v[180:181]
	v_pk_fma_f32 v[166:167], v[166:167], v[162:163], v[190:191]
	v_pk_fma_f32 v[176:177], v[134:135], v[238:239], v[176:177]
	v_pk_fma_f32 v[180:181], v[158:159], v[154:155], v[180:181]
	v_pk_fma_f32 v[166:167], v[158:159], v[170:171], v[166:167]
	v_pk_fma_f32 v[158:159], v[158:159], v[162:163], v[190:191]
	v_pk_fma_f32 v[176:177], v[186:187], v[138:139], v[176:177]
	v_pk_fma_f32 v[166:167], v[150:151], v[154:155], v[166:167]
	v_pk_fma_f32 v[150:151], v[150:151], v[170:171], v[158:159]
	v_pk_fma_f32 v[228:229], v[130:131], v[238:239], v[146:147]
	v_pk_fma_f32 v[142:143], v[142:143], v[154:155], v[150:151]
	v_pk_mul_f32 v[150:151], v[176:177], v[176:177]
	v_pk_fma_f32 v[228:229], v[186:187], v[134:135], v[228:229]
	v_pk_fma_f32 v[150:151], v[150:151], s[20:21], v[172:173] op_sel_hi:[1,0,0]
	v_pk_fma_f32 v[186:187], v[186:187], v[130:131], v[146:147]
	v_pk_mul_f32 v[150:151], v[176:177], v[150:151]
	v_pk_fma_f32 v[186:187], v[182:183], v[134:135], v[186:187]
	v_exp_f32_e32 v150, v150
	v_exp_f32_e32 v151, v151
	v_pk_fma_f32 v[186:187], v[178:179], v[138:139], v[186:187]
	v_pk_fma_f32 v[228:229], v[182:183], v[138:139], v[228:229]
	v_pk_fma_f32 v[182:183], v[182:183], v[130:131], v[146:147]
	v_pk_add_f32 v[150:151], v[150:151], 1.0 op_sel_hi:[1,0]
	v_pk_fma_f32 v[178:179], v[178:179], v[134:135], v[182:183]
	v_rcp_f32_e32 v150, v150
	v_rcp_f32_e32 v151, v151
	v_pk_fma_f32 v[174:175], v[174:175], v[138:139], v[178:179]
	v_pk_mul_f32 v[158:159], v[228:229], v[228:229]
	v_cvt_pk_bf16_f32 v156, v156, v157
	v_pk_fma_f32 v[150:151], v[176:177], v[150:151], v[176:177] neg_lo:[1,0,0] neg_hi:[1,0,0]
	v_pk_mul_f32 v[176:177], v[186:187], v[186:187]
	v_pk_fma_f32 v[158:159], v[158:159], s[20:21], v[172:173] op_sel_hi:[1,0,0]
	v_pk_fma_f32 v[176:177], v[176:177], s[20:21], v[172:173] op_sel_hi:[1,0,0]
	v_pk_mul_f32 v[158:159], v[228:229], v[158:159]
	v_pk_mul_f32 v[176:177], v[186:187], v[176:177]
	v_exp_f32_e32 v158, v158
	v_exp_f32_e32 v176, v176
	v_exp_f32_e32 v177, v177
	v_exp_f32_e32 v159, v159
	v_pk_mul_f32 v[150:151], v[184:185], v[150:151]
	v_cvt_pk_bf16_f32 v140, v140, v141
	v_pk_add_f32 v[176:177], v[176:177], 1.0 op_sel_hi:[1,0]
	v_pk_add_f32 v[158:159], v[158:159], 1.0 op_sel_hi:[1,0]
	v_rcp_f32_e32 v176, v176
	v_rcp_f32_e32 v177, v177
	v_rcp_f32_e32 v158, v158
	v_rcp_f32_e32 v159, v159
	v_cvt_pk_bf16_f32 v165, v150, v151
	v_pk_fma_f32 v[176:177], v[186:187], v[176:177], v[186:187] neg_lo:[1,0,0] neg_hi:[1,0,0]
	v_pk_fma_f32 v[158:159], v[228:229], v[158:159], v[228:229] neg_lo:[1,0,0] neg_hi:[1,0,0]
	v_pk_mul_f32 v[166:167], v[166:167], v[176:177]
	v_pk_mul_f32 v[176:177], v[174:175], v[174:175]
	v_pk_mul_f32 v[158:159], v[180:181], v[158:159]
	v_pk_fma_f32 v[176:177], v[176:177], s[20:21], v[172:173] op_sel_hi:[1,0,0]
	v_cvt_pk_bf16_f32 v157, v158, v159
	v_cvt_pk_bf16_f32 v149, v166, v167
	s_nop 0
	v_pk_mul_f32 v[176:177], v[174:175], v[176:177]
	s_nop 0
	v_exp_f32_e32 v176, v176
	v_exp_f32_e32 v177, v177
	s_nop 0
	v_pk_add_f32 v[176:177], v[176:177], 1.0 op_sel_hi:[1,0]
	s_nop 0
	v_rcp_f32_e32 v176, v176
	v_rcp_f32_e32 v177, v177
	s_nop 0
	v_pk_fma_f32 v[174:175], v[174:175], v[176:177], v[174:175] neg_lo:[1,0,0] neg_hi:[1,0,0]
	s_nop 0
	v_pk_mul_f32 v[142:143], v[142:143], v[174:175]
	s_nop 0
	v_cvt_pk_bf16_f32 v141, v142, v143
	ds_read2_b32 v[142:143], v223 offset0:32 offset1:36
	ds_read2_b32 v[150:151], v223 offset0:40 offset1:44
	ds_read2_b32 v[158:159], v223 offset0:96 offset1:100
	ds_read2_b32 v[166:167], v223 offset0:104 offset1:108
	s_waitcnt lgkmcnt(3)
	v_mov_b32_dpp v143, v80 row_shr:1 row_mask:0xf bank_mask:0xf
	s_waitcnt lgkmcnt(2)
	v_mov_b32_dpp v150, v85 row_shr:1 row_mask:0xf bank_mask:0xf
	v_mov_b32_dpp v151, v81 row_shr:1 row_mask:0xf bank_mask:0xf
	v_mov_b32_e32 v174, v143
	v_mov_b32_dpp v142, v84 row_shr:1 row_mask:0xf bank_mask:0xf
	v_mov_b32_e32 v143, v150
	v_mov_b32_e32 v175, v151
	s_waitcnt lgkmcnt(1)
	v_mov_b32_dpp v159, v64 row_shr:1 row_mask:0xf bank_mask:0xf
	s_waitcnt lgkmcnt(0)
;     __device__ __forceinline__ void operator()(const f32x4 (&acc)[2][2][4][2], const Unit& u, int wr, int wc, int fr, int fq) const {
;     ...
;             for (int n = 0; n < 2; ++n) {
;                 const f32x4 wg0 = wgt[n][0], wg1 = wgt[n][1], wg2 = wgt[n][2], bg = wgt[n][3], wv0 = wgt[n][4], wv1 = wgt[n][5], wv2 = wgt[n][6], bv = wgt[n][7];
; #pragma unroll
;                 for (int jp = 0; jp < 2; ++jp) {
;                     const int ja = 2 * jp, jb = 2 * jp + 1;
;                     const int vga = ((0 * 2 + n) * 4 + ja) * 2, vgb = ((0 * 2 + n) * 4 + jb) * 2, vva = ((1 * 2 + n) * 4 + ja) * 2, vvb = ((1 * 2 + n) * 4 + jb) * 2;
;                     const float hg2a = hl[vga * 4], hg1a = hl[(vga + 1) * 4], hg2b = hl[vgb * 4], hg1b = hl[(vgb + 1) * 4];
;                     const float hv2a = hl[vva * 4], hv1a = hl[(vva + 1) * 4], hv2b = hl[vvb * 4], hv1b = hl[(vvb + 1) * 4];
;     ...
;                     const f32x2 g0 = UC_PAIR(0, 0), g1 = UC_PAIR(0, 1), g2 = UC_PAIR(0, 2), g3 = UC_PAIR(0, 3);
;                     const f32x2 v0 = UC_PAIR(1, 0), v1 = UC_PAIR(1, 1), v2 = UC_PAIR(1, 2), v3 = UC_PAIR(1, 3);
;     ...
;                     f32x2 gp1, gp2, vp1, vp2;
;                     gp1.x = dpp_shr1_keep(hg1a, g3.x); gp1.y = dpp_shr1_keep(hg1b, g3.y); gp2.x = dpp_shr1_keep(hg2a, g2.x); gp2.y = dpp_shr1_keep(hg2b, g2.y);
;                     vp1.x = dpp_shr1_keep(hv1a, v3.x); vp1.y = dpp_shr1_keep(hv1b, v3.y); vp2.x = dpp_shr1_keep(hv2a, v2.x); vp2.y = dpp_shr1_keep(hv2b, v2.y);
;                     const f32x2 a0 = jp == 0 ? lo2(wg0) : hi2(wg0), a1 = jp == 0 ? lo2(wg1) : hi2(wg1), a2 = jp == 0 ? lo2(wg2) : hi2(wg2), ab = jp == 0 ? lo2(bg) : hi2(bg);
;                     const f32x2 c0 = jp == 0 ? lo2(wv0) : hi2(wv0), c1 = jp == 0 ? lo2(wv1) : hi2(wv1), c2 = jp == 0 ? lo2(wv2) : hi2(wv2), cb_ = jp == 0 ? lo2(bv) : hi2(bv);
;                     const f32x2 yg0 = ab + a0 * gp2 + a1 * gp1 + a2 * g0, yv0 = cb_ + c0 * vp2 + c1 * vp1 + c2 * v0;
;                     const f32x2 yg1 = ab + a0 * gp1 + a1 * g0 + a2 * g1, yv1 = cb_ + c0 * vp1 + c1 * v0 + c2 * v1;
;                     const f32x2 yg2 = ab + a0 * g0 + a1 * g1 + a2 * g2, yv2 = cb_ + c0 * v0 + c1 * v1 + c2 * v2;
;                     const f32x2 yg3 = ab + a0 * g1 + a1 * g2 + a2 * g3, yv3 = cb_ + c0 * v1 + c1 * v2 + c2 * v3;
	v_mov_b32_dpp v167, v65 row_shr:1 row_mask:0xf bank_mask:0xf
	v_mov_b32_dpp v166, v69 row_shr:1 row_mask:0xf bank_mask:0xf
	v_pk_fma_f32 v[142:143], v[96:97], v[142:143], v[108:109]
	v_mov_b32_e32 v150, v159
	v_mov_b32_e32 v151, v167
	v_mov_b32_e32 v159, v166
	v_pk_fma_f32 v[142:143], v[100:101], v[174:175], v[142:143]
	v_pk_fma_f32 v[166:167], v[96:97], v[174:175], v[108:109]
	v_pk_fma_f32 v[142:143], v[92:93], v[104:105], v[142:143]
	v_pk_fma_f32 v[166:167], v[92:93], v[100:101], v[166:167]
	v_pk_fma_f32 v[92:93], v[92:93], v[96:97], v[108:109]
	v_pk_fma_f32 v[166:167], v[88:89], v[104:105], v[166:167]
	v_pk_fma_f32 v[92:93], v[88:89], v[100:101], v[92:93]
	v_pk_fma_f32 v[88:89], v[88:89], v[96:97], v[108:109]
	v_pk_fma_f32 v[92:93], v[84:85], v[104:105], v[92:93]
	v_pk_fma_f32 v[84:85], v[84:85], v[100:101], v[88:89]
	v_mov_b32_dpp v158, v68 row_shr:1 row_mask:0xf bank_mask:0xf
	v_pk_fma_f32 v[80:81], v[80:81], v[104:105], v[84:85]
	v_pk_mul_f32 v[84:85], v[92:93], v[92:93]
	v_pk_fma_f32 v[158:159], v[116:117], v[158:159], v[124:125]
	v_pk_fma_f32 v[84:85], v[84:85], s[20:21], v[172:173] op_sel_hi:[1,0,0]
	v_pk_fma_f32 v[158:159], v[120:121], v[150:151], v[158:159]
	v_pk_mul_f32 v[84:85], v[92:93], v[84:85]
	v_pk_fma_f32 v[150:151], v[116:117], v[150:151], v[124:125]
	v_exp_f32_e32 v84, v84
	v_exp_f32_e32 v85, v85
	v_pk_fma_f32 v[158:159], v[76:77], v[112:113], v[158:159]
	v_pk_fma_f32 v[150:151], v[76:77], v[120:121], v[150:151]
	v_pk_fma_f32 v[76:77], v[76:77], v[116:117], v[124:125]
	v_pk_add_f32 v[84:85], v[84:85], 1.0 op_sel_hi:[1,0]
	v_pk_fma_f32 v[150:151], v[72:73], v[112:113], v[150:151]
	v_rcp_f32_e32 v84, v84
	v_rcp_f32_e32 v85, v85
	v_pk_fma_f32 v[76:77], v[72:73], v[120:121], v[76:77]
	v_pk_fma_f32 v[72:73], v[72:73], v[116:117], v[124:125]
	v_pk_fma_f32 v[76:77], v[68:69], v[112:113], v[76:77]
	v_pk_fma_f32 v[68:69], v[68:69], v[120:121], v[72:73]
	v_pk_fma_f32 v[84:85], v[92:93], v[84:85], v[92:93] neg_lo:[1,0,0] neg_hi:[1,0,0]
	v_pk_fma_f32 v[64:65], v[64:65], v[112:113], v[68:69]
	v_pk_mul_f32 v[68:69], v[142:143], v[142:143]
	v_pk_mul_f32 v[72:73], v[166:167], v[166:167]
	v_pk_mul_f32 v[76:77], v[76:77], v[84:85]
	v_pk_mul_f32 v[84:85], v[80:81], v[80:81]
	v_pk_fma_f32 v[68:69], v[68:69], s[20:21], v[172:173] op_sel_hi:[1,0,0]
	v_pk_fma_f32 v[72:73], v[72:73], s[20:21], v[172:173] op_sel_hi:[1,0,0]
	v_pk_fma_f32 v[84:85], v[84:85], s[20:21], v[172:173] op_sel_hi:[1,0,0]
	v_pk_mul_f32 v[68:69], v[142:143], v[68:69]
	v_pk_mul_f32 v[72:73], v[166:167], v[72:73]
	v_pk_mul_f32 v[84:85], v[80:81], v[84:85]
	v_exp_f32_e32 v68, v68
	v_exp_f32_e32 v69, v69
	v_exp_f32_e32 v72, v72
	v_exp_f32_e32 v73, v73
	v_exp_f32_e32 v84, v84
	v_exp_f32_e32 v85, v85
	v_pk_add_f32 v[68:69], v[68:69], 1.0 op_sel_hi:[1,0]
	v_pk_add_f32 v[72:73], v[72:73], 1.0 op_sel_hi:[1,0]
	v_rcp_f32_e32 v68, v68
	v_pk_add_f32 v[84:85], v[84:85], 1.0 op_sel_hi:[1,0]
	v_rcp_f32_e32 v69, v69
	v_rcp_f32_e32 v72, v72
	v_rcp_f32_e32 v73, v73
	v_rcp_f32_e32 v84, v84
	v_rcp_f32_e32 v85, v85
	v_pk_fma_f32 v[68:69], v[142:143], v[68:69], v[142:143] neg_lo:[1,0,0] neg_hi:[1,0,0]
	v_pk_fma_f32 v[72:73], v[166:167], v[72:73], v[166:167] neg_lo:[1,0,0] neg_hi:[1,0,0]
	v_pk_mul_f32 v[68:69], v[158:159], v[68:69]
	v_pk_fma_f32 v[80:81], v[80:81], v[84:85], v[80:81] neg_lo:[1,0,0] neg_hi:[1,0,0]
	v_pk_mul_f32 v[72:73], v[150:151], v[72:73]
	v_pk_mul_f32 v[64:65], v[64:65], v[80:81]
	v_cvt_pk_bf16_f32 v166, v68, v69
	v_cvt_pk_bf16_f32 v158, v72, v73
	v_cvt_pk_bf16_f32 v150, v76, v77
	v_pk_fma_f32 v[84:85], v[90:91], v[98:99], v[110:111]
	v_cvt_pk_bf16_f32 v142, v64, v65
	ds_read2_b32 v[64:65], v223 offset0:48 offset1:52
	ds_read2_b32 v[68:69], v223 offset0:56 offset1:60
	ds_read2_b32 v[72:73], v223 offset0:112 offset1:116
	ds_read2_b32 v[76:77], v223 offset0:120 offset1:124
	v_pk_fma_f32 v[84:85], v[86:87], v[102:103], v[84:85]
	s_waitcnt lgkmcnt(3)
	v_mov_b32_dpp v65, v82 row_shr:1 row_mask:0xf bank_mask:0xf
	s_waitcnt lgkmcnt(2)
	v_mov_b32_dpp v68, v87 row_shr:1 row_mask:0xf bank_mask:0xf
	s_waitcnt lgkmcnt(1)
	v_mov_b32_dpp v73, v66 row_shr:1 row_mask:0xf bank_mask:0xf
	s_waitcnt lgkmcnt(0)
	v_mov_b32_dpp v76, v71 row_shr:1 row_mask:0xf bank_mask:0xf
	v_mov_b32_dpp v69, v83 row_shr:1 row_mask:0xf bank_mask:0xf
	v_mov_b32_e32 v80, v65
	v_mov_b32_e32 v65, v68
	v_mov_b32_dpp v77, v67 row_shr:1 row_mask:0xf bank_mask:0xf
	v_mov_b32_e32 v68, v73
	v_mov_b32_dpp v72, v70 row_shr:1 row_mask:0xf bank_mask:0xf
	v_mov_b32_e32 v73, v76
	v_mov_b32_e32 v81, v69
	v_mov_b32_e32 v69, v77
	v_pk_fma_f32 v[72:73], v[118:119], v[72:73], v[126:127]
	v_mov_b32_dpp v64, v86 row_shr:1 row_mask:0xf bank_mask:0xf
	v_pk_fma_f32 v[72:73], v[122:123], v[68:69], v[72:73]
	v_pk_fma_f32 v[68:69], v[118:119], v[68:69], v[126:127]
	v_pk_fma_f32 v[64:65], v[98:99], v[64:65], v[110:111]
	v_pk_fma_f32 v[72:73], v[78:79], v[114:115], v[72:73]
	v_pk_fma_f32 v[68:69], v[78:79], v[122:123], v[68:69]
	v_pk_fma_f32 v[78:79], v[78:79], v[118:119], v[126:127]
	v_pk_fma_f32 v[64:65], v[102:103], v[80:81], v[64:65]
	v_pk_fma_f32 v[68:69], v[74:75], v[114:115], v[68:69]
	v_pk_fma_f32 v[78:79], v[74:75], v[122:123], v[78:79]
	v_pk_fma_f32 v[74:75], v[74:75], v[118:119], v[126:127]
	v_pk_fma_f32 v[64:65], v[94:95], v[106:107], v[64:65]
	v_pk_fma_f32 v[78:79], v[70:71], v[114:115], v[78:79]
	v_pk_fma_f32 v[70:71], v[70:71], v[122:123], v[74:75]
	v_pk_fma_f32 v[76:77], v[98:99], v[80:81], v[110:111]
	v_pk_fma_f32 v[66:67], v[66:67], v[114:115], v[70:71]
	v_pk_mul_f32 v[70:71], v[64:65], v[64:65]
	v_pk_fma_f32 v[76:77], v[94:95], v[102:103], v[76:77]
	v_pk_fma_f32 v[70:71], v[70:71], s[20:21], v[172:173] op_sel_hi:[1,0,0]
;     __device__ __forceinline__ void operator()(const f32x4 (&acc)[2][2][4][2], const Unit& u, int wr, int wc, int fr, int fq) const {
;     ...
;             for (int n = 0; n < 2; ++n) {
;                 const f32x4 wg0 = wgt[n][0], wg1 = wgt[n][1], wg2 = wgt[n][2], bg = wgt[n][3], wv0 = wgt[n][4], wv1 = wgt[n][5], wv2 = wgt[n][6], bv = wgt[n][7];
; #pragma unroll
;                 for (int jp = 0; jp < 2; ++jp) {
;                     const int ja = 2 * jp, jb = 2 * jp + 1;
;                     const int vga = ((0 * 2 + n) * 4 + ja) * 2, vgb = ((0 * 2 + n) * 4 + jb) * 2, vva = ((1 * 2 + n) * 4 + ja) * 2, vvb = ((1 * 2 + n) * 4 + jb) * 2;
;                     const float hg2a = hl[vga * 4], hg1a = hl[(vga + 1) * 4], hg2b = hl[vgb * 4], hg1b = hl[(vgb + 1) * 4];
;                     const float hv2a = hl[vva * 4], hv1a = hl[(vva + 1) * 4], hv2b = hl[vvb * 4], hv1b = hl[(vvb + 1) * 4];
;     ...
;                     const f32x2 g0 = UC_PAIR(0, 0), g1 = UC_PAIR(0, 1), g2 = UC_PAIR(0, 2), g3 = UC_PAIR(0, 3);
;                     const f32x2 v0 = UC_PAIR(1, 0), v1 = UC_PAIR(1, 1), v2 = UC_PAIR(1, 2), v3 = UC_PAIR(1, 3);
;     ...
;                     f32x2 gp1, gp2, vp1, vp2;
;                     gp1.x = dpp_shr1_keep(hg1a, g3.x); gp1.y = dpp_shr1_keep(hg1b, g3.y); gp2.x = dpp_shr1_keep(hg2a, g2.x); gp2.y = dpp_shr1_keep(hg2b, g2.y);
;                     vp1.x = dpp_shr1_keep(hv1a, v3.x); vp1.y = dpp_shr1_keep(hv1b, v3.y); vp2.x = dpp_shr1_keep(hv2a, v2.x); vp2.y = dpp_shr1_keep(hv2b, v2.y);
;     ...
;                     const f32x2 r0 = gelu_tanh_fast2(yg0) * yv0, r1 = gelu_tanh_fast2(yg1) * yv1, r2 = gelu_tanh_fast2(yg2) * yv2, r3 = gelu_tanh_fast2(yg3) * yv3;
;                     const unsigned q0 = cvt_pk_bf16(r0.x, r0.y), q1 = cvt_pk_bf16(r1.x, r1.y), q2 = cvt_pk_bf16(r2.x, r2.y), q3 = cvt_pk_bf16(r3.x, r3.y);
;                     if (jp == 0) { pk[0][n].x = q0; pk[1][n].x = q1; pk[2][n].x = q2; pk[3][n].x = q3; } else { pk[0][n].y = q0; pk[1][n].y = q1; pk[2][n].y = q2; pk[3][n].y = q3; }
;                 }
;             }
;             bf16_t* op = ACT + (size_t)(tok0 + ai * HALF) * DFF + ch0;
;             const bool top = (ai == 0) && (wr == 0) && (fr == 0);
; #pragma unroll
;             for (int m = 0; m < 4; ++m) { const u32x4 w = (u32x4){pk[m][0].x, pk[m][0].y, pk[m][1].x, pk[m][1].y};
;                 if (!(top && m < 2)) *(u32x4*)(op + (size_t)m * DFF) = w; }
	v_pk_fma_f32 v[76:77], v[90:91], v[106:107], v[76:77]
	v_pk_mul_f32 v[70:71], v[64:65], v[70:71]
	v_pk_fma_f32 v[80:81], v[94:95], v[98:99], v[110:111]
	v_exp_f32_e32 v70, v70
	v_exp_f32_e32 v71, v71
	v_pk_fma_f32 v[80:81], v[90:91], v[102:103], v[80:81]
	v_pk_fma_f32 v[82:83], v[82:83], v[106:107], v[84:85]
	v_pk_fma_f32 v[80:81], v[86:87], v[106:107], v[80:81]
	v_pk_add_f32 v[70:71], v[70:71], 1.0 op_sel_hi:[1,0]
	s_nop 0
	v_rcp_f32_e32 v70, v70
	v_rcp_f32_e32 v71, v71
	s_nop 0
	v_pk_fma_f32 v[64:65], v[64:65], v[70:71], v[64:65] neg_lo:[1,0,0] neg_hi:[1,0,0]
	v_pk_mul_f32 v[70:71], v[76:77], v[76:77]
	v_pk_mul_f32 v[64:65], v[72:73], v[64:65]
	v_pk_fma_f32 v[70:71], v[70:71], s[20:21], v[172:173] op_sel_hi:[1,0,0]
	v_pk_mul_f32 v[72:73], v[82:83], v[82:83]
	v_pk_mul_f32 v[70:71], v[76:77], v[70:71]
	v_pk_fma_f32 v[72:73], v[72:73], s[20:21], v[172:173] op_sel_hi:[1,0,0]
	v_exp_f32_e32 v70, v70
	v_exp_f32_e32 v71, v71
	v_pk_mul_f32 v[72:73], v[82:83], v[72:73]
	v_cvt_pk_bf16_f32 v167, v64, v65
	v_mov_b64_e32 v[64:65], s[82:83]
	v_pk_add_f32 v[70:71], v[70:71], 1.0 op_sel_hi:[1,0]
	v_exp_f32_e32 v72, v72
	v_rcp_f32_e32 v70, v70
	v_rcp_f32_e32 v71, v71
	v_exp_f32_e32 v73, v73
	v_pk_fma_f32 v[70:71], v[76:77], v[70:71], v[76:77] neg_lo:[1,0,0] neg_hi:[1,0,0]
	s_nop 0
	v_pk_mul_f32 v[68:69], v[68:69], v[70:71]
	v_pk_mul_f32 v[70:71], v[80:81], v[80:81]
	v_pk_add_f32 v[72:73], v[72:73], 1.0 op_sel_hi:[1,0]
	v_pk_fma_f32 v[70:71], v[70:71], s[20:21], v[172:173] op_sel_hi:[1,0,0]
	v_rcp_f32_e32 v72, v72
	v_pk_mul_f32 v[70:71], v[80:81], v[70:71]
	v_rcp_f32_e32 v73, v73
	v_exp_f32_e32 v70, v70
	v_exp_f32_e32 v71, v71
	v_mad_i64_i32 v[64:65], s[20:21], v226, s73, v[64:65]
	v_pk_fma_f32 v[72:73], v[82:83], v[72:73], v[82:83] neg_lo:[1,0,0] neg_hi:[1,0,0]
	v_pk_add_f32 v[70:71], v[70:71], 1.0 op_sel_hi:[1,0]
	v_lshl_add_u64 v[64:65], v[220:221], 1, v[64:65]
	v_rcp_f32_e32 v70, v70
	v_rcp_f32_e32 v71, v71
	v_pk_mul_f32 v[66:67], v[66:67], v[72:73]
	v_cvt_pk_bf16_f32 v159, v68, v69
	v_pk_fma_f32 v[70:71], v[80:81], v[70:71], v[80:81] neg_lo:[1,0,0] neg_hi:[1,0,0]
	s_nop 0
	v_pk_mul_f32 v[70:71], v[78:79], v[70:71]
	v_cvt_pk_bf16_f32 v143, v66, v67
	s_nop 0
	v_cvt_pk_bf16_f32 v151, v70, v71
	s_and_saveexec_b64 s[20:21], s[44:45]
	s_cbranch_execz .LBB0_539
	v_add_co_u32_e32 v66, vcc, 0x2000, v64
	global_store_dwordx4 v[64:65], v[164:167], off sc1
	s_nop 0
	v_addc_co_u32_e32 v67, vcc, 0, v65, vcc
	global_store_dwordx4 v[66:67], v[156:159], off offset:3072 sc1
.LBB0_539:
	s_or_b64 exec, exec, s[20:21]
	s_movk_i32 s13, 0x5000
	v_add_co_u32_e32 v66, vcc, s13, v64
	s_mov_b32 s20, 0x40135761
	s_nop 0
	v_addc_co_u32_e32 v67, vcc, 0, v65, vcc
	v_add_co_u32_e32 v64, vcc, s74, v64
	global_store_dwordx4 v[66:67], v[148:151], off offset:2048 sc1
	s_nop 0
	v_addc_co_u32_e32 v65, vcc, 0, v65, vcc
	ds_read2_b32 v[66:67], v225 offset1:4
	ds_read2_b32 v[68:69], v225 offset0:8 offset1:12
	global_store_dwordx4 v[64:65], v[140:143], off offset:1024 sc1
	ds_read2_b32 v[64:65], v225 offset0:64 offset1:68
	ds_read2_b32 v[70:71], v225 offset0:72 offset1:76
	s_waitcnt lgkmcnt(3)
	v_mov_b32_dpp v67, v48 row_shr:1 row_mask:0xf bank_mask:0xf
	s_waitcnt lgkmcnt(2)
	v_mov_b32_dpp v68, v53 row_shr:1 row_mask:0xf bank_mask:0xf
	v_mov_b32_dpp v69, v49 row_shr:1 row_mask:0xf bank_mask:0xf
	v_mov_b32_e32 v72, v67
	v_mov_b32_dpp v66, v52 row_shr:1 row_mask:0xf bank_mask:0xf
	v_mov_b32_e32 v67, v68
	s_waitcnt lgkmcnt(1)
	v_mov_b32_dpp v65, v32 row_shr:1 row_mask:0xf bank_mask:0xf
	s_waitcnt lgkmcnt(0)
	v_mov_b32_dpp v70, v37 row_shr:1 row_mask:0xf bank_mask:0xf
	v_mov_b32_e32 v73, v69
	v_mov_b32_dpp v71, v33 row_shr:1 row_mask:0xf bank_mask:0xf
	v_mov_b32_e32 v68, v65
	v_mov_b32_dpp v64, v36 row_shr:1 row_mask:0xf bank_mask:0xf
	v_mov_b32_e32 v65, v70
	v_pk_fma_f32 v[66:67], v[128:129], v[66:67], v[144:145]
	v_mov_b32_e32 v69, v71
	v_pk_fma_f32 v[66:67], v[132:133], v[72:73], v[66:67]
	v_pk_fma_f32 v[64:65], v[160:161], v[64:65], v[188:189]
	v_pk_fma_f32 v[70:71], v[128:129], v[72:73], v[144:145]
	v_pk_fma_f32 v[66:67], v[60:61], v[136:137], v[66:67]
	v_pk_fma_f32 v[64:65], v[168:169], v[68:69], v[64:65]
	v_pk_fma_f32 v[70:71], v[60:61], v[132:133], v[70:71]
	v_pk_fma_f32 v[68:69], v[160:161], v[68:69], v[188:189]
	v_pk_fma_f32 v[60:61], v[60:61], v[128:129], v[144:145]
	v_pk_fma_f32 v[64:65], v[44:45], v[152:153], v[64:65]
	v_pk_fma_f32 v[70:71], v[56:57], v[136:137], v[70:71]
	v_pk_fma_f32 v[68:69], v[44:45], v[168:169], v[68:69]
	v_pk_fma_f32 v[60:61], v[56:57], v[132:133], v[60:61]
	v_pk_fma_f32 v[44:45], v[44:45], v[160:161], v[188:189]
	v_pk_fma_f32 v[56:57], v[56:57], v[128:129], v[144:145]
	v_pk_fma_f32 v[68:69], v[40:41], v[152:153], v[68:69]
	v_pk_fma_f32 v[60:61], v[52:53], v[136:137], v[60:61]
	v_pk_fma_f32 v[44:45], v[40:41], v[168:169], v[44:45]
	v_pk_fma_f32 v[52:53], v[52:53], v[132:133], v[56:57]
	v_pk_fma_f32 v[40:41], v[40:41], v[160:161], v[188:189]
	v_pk_fma_f32 v[44:45], v[36:37], v[152:153], v[44:45]
	v_pk_fma_f32 v[52:53], v[48:49], v[136:137], v[52:53]
	v_pk_fma_f32 v[36:37], v[36:37], v[168:169], v[40:41]
	v_pk_mul_f32 v[40:41], v[66:67], v[66:67]
	v_mov_b64_e32 v[48:49], s[20:21]
	s_mov_b32 s20, 0x3dd2d3e7
	v_pk_mul_f32 v[56:57], v[70:71], v[70:71]
	v_pk_fma_f32 v[40:41], v[40:41], s[20:21], v[48:49] op_sel_hi:[1,0,0]
	v_pk_fma_f32 v[56:57], v[56:57], s[20:21], v[48:49] op_sel_hi:[1,0,0]
	v_pk_mul_f32 v[40:41], v[66:67], v[40:41]
	v_pk_mul_f32 v[56:57], v[70:71], v[56:57]
	v_exp_f32_e32 v40, v40
	v_exp_f32_e32 v41, v41
	v_exp_f32_e32 v56, v56
	v_exp_f32_e32 v57, v57
	v_pk_fma_f32 v[32:33], v[32:33], v[152:153], v[36:37]
	v_pk_add_f32 v[40:41], v[40:41], 1.0 op_sel_hi:[1,0]
;     __device__ __forceinline__ void operator()(const f32x4 (&acc)[2][2][4][2], const Unit& u, int wr, int wc, int fr, int fq) const {
;     ...
;             for (int n = 0; n < 2; ++n) {
;                 const f32x4 wg0 = wgt[n][0], wg1 = wgt[n][1], wg2 = wgt[n][2], bg = wgt[n][3], wv0 = wgt[n][4], wv1 = wgt[n][5], wv2 = wgt[n][6], bv = wgt[n][7];
; #pragma unroll
;                 for (int jp = 0; jp < 2; ++jp) {
;                     const int ja = 2 * jp, jb = 2 * jp + 1;
;                     const int vga = ((0 * 2 + n) * 4 + ja) * 2, vgb = ((0 * 2 + n) * 4 + jb) * 2, vva = ((1 * 2 + n) * 4 + ja) * 2, vvb = ((1 * 2 + n) * 4 + jb) * 2;
;                     const float hg2a = hl[vga * 4], hg1a = hl[(vga + 1) * 4], hg2b = hl[vgb * 4], hg1b = hl[(vgb + 1) * 4];
;                     const float hv2a = hl[vva * 4], hv1a = hl[(vva + 1) * 4], hv2b = hl[vvb * 4], hv1b = hl[(vvb + 1) * 4];
;     ...
;                     const f32x2 g0 = UC_PAIR(0, 0), g1 = UC_PAIR(0, 1), g2 = UC_PAIR(0, 2), g3 = UC_PAIR(0, 3);
;                     const f32x2 v0 = UC_PAIR(1, 0), v1 = UC_PAIR(1, 1), v2 = UC_PAIR(1, 2), v3 = UC_PAIR(1, 3);
;     ...
;                     f32x2 gp1, gp2, vp1, vp2;
;                     gp1.x = dpp_shr1_keep(hg1a, g3.x); gp1.y = dpp_shr1_keep(hg1b, g3.y); gp2.x = dpp_shr1_keep(hg2a, g2.x); gp2.y = dpp_shr1_keep(hg2b, g2.y);
;                     vp1.x = dpp_shr1_keep(hv1a, v3.x); vp1.y = dpp_shr1_keep(hv1b, v3.y); vp2.x = dpp_shr1_keep(hv2a, v2.x); vp2.y = dpp_shr1_keep(hv2b, v2.y);
;                     const f32x2 a0 = jp == 0 ? lo2(wg0) : hi2(wg0), a1 = jp == 0 ? lo2(wg1) : hi2(wg1), a2 = jp == 0 ? lo2(wg2) : hi2(wg2), ab = jp == 0 ? lo2(bg) : hi2(bg);
;                     const f32x2 c0 = jp == 0 ? lo2(wv0) : hi2(wv0), c1 = jp == 0 ? lo2(wv1) : hi2(wv1), c2 = jp == 0 ? lo2(wv2) : hi2(wv2), cb_ = jp == 0 ? lo2(bv) : hi2(bv);
;                     const f32x2 yg0 = ab + a0 * gp2 + a1 * gp1 + a2 * g0, yv0 = cb_ + c0 * vp2 + c1 * vp1 + c2 * v0;
;                     const f32x2 yg1 = ab + a0 * gp1 + a1 * g0 + a2 * g1, yv1 = cb_ + c0 * vp1 + c1 * v0 + c2 * v1;
;                     const f32x2 yg2 = ab + a0 * g0 + a1 * g1 + a2 * g2, yv2 = cb_ + c0 * v0 + c1 * v1 + c2 * v2;
;                     const f32x2 yg3 = ab + a0 * g1 + a1 * g2 + a2 * g3, yv3 = cb_ + c0 * v1 + c1 * v2 + c2 * v3;
	v_pk_add_f32 v[56:57], v[56:57], 1.0 op_sel_hi:[1,0]
	v_rcp_f32_e32 v40, v40
	v_rcp_f32_e32 v41, v41
	v_rcp_f32_e32 v56, v56
	v_rcp_f32_e32 v57, v57
	v_pk_fma_f32 v[36:37], v[66:67], v[40:41], v[66:67] neg_lo:[1,0,0] neg_hi:[1,0,0]
	s_nop 0
	v_pk_mul_f32 v[36:37], v[64:65], v[36:37]
	v_pk_fma_f32 v[40:41], v[70:71], v[56:57], v[70:71] neg_lo:[1,0,0] neg_hi:[1,0,0]
	v_pk_mul_f32 v[56:57], v[60:61], v[60:61]
	v_pk_mul_f32 v[64:65], v[52:53], v[52:53]
	v_pk_fma_f32 v[56:57], v[56:57], s[20:21], v[48:49] op_sel_hi:[1,0,0]
	v_pk_fma_f32 v[64:65], v[64:65], s[20:21], v[48:49] op_sel_hi:[1,0,0]
	v_pk_mul_f32 v[56:57], v[60:61], v[56:57]
	v_pk_mul_f32 v[64:65], v[52:53], v[64:65]
	v_exp_f32_e32 v56, v56
	v_exp_f32_e32 v57, v57
	v_exp_f32_e32 v64, v64
	v_exp_f32_e32 v65, v65
	v_pk_mul_f32 v[40:41], v[68:69], v[40:41]
	v_pk_add_f32 v[56:57], v[56:57], 1.0 op_sel_hi:[1,0]
	v_cvt_pk_bf16_f32 v40, v40, v41
	v_pk_add_f32 v[64:65], v[64:65], 1.0 op_sel_hi:[1,0]
	v_rcp_f32_e32 v56, v56
	v_rcp_f32_e32 v57, v57
	v_rcp_f32_e32 v64, v64
	v_rcp_f32_e32 v65, v65
	v_pk_fma_f32 v[56:57], v[60:61], v[56:57], v[60:61] neg_lo:[1,0,0] neg_hi:[1,0,0]
	s_nop 0
	v_pk_mul_f32 v[56:57], v[44:45], v[56:57]
	v_pk_fma_f32 v[44:45], v[52:53], v[64:65], v[52:53] neg_lo:[1,0,0] neg_hi:[1,0,0]
	s_nop 0
	v_pk_mul_f32 v[32:33], v[32:33], v[44:45]
	v_cvt_pk_bf16_f32 v44, v36, v37
	v_cvt_pk_bf16_f32 v36, v56, v57
	ds_read2_b32 v[52:53], v225 offset0:16 offset1:20
	ds_read2_b32 v[56:57], v225 offset0:24 offset1:28
	ds_read2_b32 v[60:61], v225 offset0:80 offset1:84
	ds_read2_b32 v[64:65], v225 offset0:88 offset1:92
	v_cvt_pk_bf16_f32 v32, v32, v33
	s_waitcnt lgkmcnt(3)
	v_mov_b32_dpp v53, v50 row_shr:1 row_mask:0xf bank_mask:0xf
	s_waitcnt lgkmcnt(2)
	v_mov_b32_dpp v56, v55 row_shr:1 row_mask:0xf bank_mask:0xf
	v_mov_b32_dpp v57, v51 row_shr:1 row_mask:0xf bank_mask:0xf
	v_mov_b32_e32 v66, v53
	v_mov_b32_dpp v52, v54 row_shr:1 row_mask:0xf bank_mask:0xf
	v_mov_b32_e32 v53, v56
	s_waitcnt lgkmcnt(1)
	v_mov_b32_dpp v61, v34 row_shr:1 row_mask:0xf bank_mask:0xf
	s_waitcnt lgkmcnt(0)
	v_mov_b32_dpp v64, v39 row_shr:1 row_mask:0xf bank_mask:0xf
	v_mov_b32_e32 v67, v57
	v_mov_b32_dpp v65, v35 row_shr:1 row_mask:0xf bank_mask:0xf
	v_mov_b32_e32 v56, v61
	v_mov_b32_dpp v60, v38 row_shr:1 row_mask:0xf bank_mask:0xf
	v_mov_b32_e32 v61, v64
	v_pk_fma_f32 v[52:53], v[130:131], v[52:53], v[146:147]
	v_mov_b32_e32 v57, v65
	v_pk_fma_f32 v[52:53], v[134:135], v[66:67], v[52:53]
	v_pk_fma_f32 v[60:61], v[162:163], v[60:61], v[190:191]
	v_pk_fma_f32 v[64:65], v[130:131], v[66:67], v[146:147]
	v_pk_fma_f32 v[52:53], v[62:63], v[138:139], v[52:53]
	v_pk_fma_f32 v[60:61], v[170:171], v[56:57], v[60:61]
	v_pk_fma_f32 v[64:65], v[62:63], v[134:135], v[64:65]
	v_pk_fma_f32 v[56:57], v[162:163], v[56:57], v[190:191]
	v_pk_fma_f32 v[62:63], v[62:63], v[130:131], v[146:147]
	v_pk_fma_f32 v[60:61], v[46:47], v[154:155], v[60:61]
	v_pk_fma_f32 v[64:65], v[58:59], v[138:139], v[64:65]
	v_pk_fma_f32 v[56:57], v[46:47], v[170:171], v[56:57]
	v_pk_fma_f32 v[62:63], v[58:59], v[134:135], v[62:63]
	v_pk_fma_f32 v[46:47], v[46:47], v[162:163], v[190:191]
	v_pk_fma_f32 v[58:59], v[58:59], v[130:131], v[146:147]
	v_pk_fma_f32 v[56:57], v[42:43], v[154:155], v[56:57]
	v_pk_fma_f32 v[62:63], v[54:55], v[138:139], v[62:63]
	v_pk_fma_f32 v[46:47], v[42:43], v[170:171], v[46:47]
	v_pk_fma_f32 v[54:55], v[54:55], v[134:135], v[58:59]
	v_pk_fma_f32 v[42:43], v[42:43], v[162:163], v[190:191]
	v_pk_fma_f32 v[46:47], v[38:39], v[154:155], v[46:47]
	v_pk_fma_f32 v[50:51], v[50:51], v[138:139], v[54:55]
	v_pk_fma_f32 v[38:39], v[38:39], v[170:171], v[42:43]
	v_pk_mul_f32 v[42:43], v[52:53], v[52:53]
	v_pk_mul_f32 v[54:55], v[64:65], v[64:65]
	v_pk_fma_f32 v[42:43], v[42:43], s[20:21], v[48:49] op_sel_hi:[1,0,0]
	v_pk_fma_f32 v[54:55], v[54:55], s[20:21], v[48:49] op_sel_hi:[1,0,0]
	v_pk_mul_f32 v[42:43], v[52:53], v[42:43]
	v_pk_mul_f32 v[54:55], v[64:65], v[54:55]
	v_exp_f32_e32 v42, v42
	v_exp_f32_e32 v43, v43
	v_exp_f32_e32 v54, v54
	v_exp_f32_e32 v55, v55
	v_pk_fma_f32 v[34:35], v[34:35], v[154:155], v[38:39]
	v_pk_add_f32 v[42:43], v[42:43], 1.0 op_sel_hi:[1,0]
	v_pk_add_f32 v[54:55], v[54:55], 1.0 op_sel_hi:[1,0]
	v_rcp_f32_e32 v42, v42
	v_rcp_f32_e32 v43, v43
	v_rcp_f32_e32 v54, v54
	v_rcp_f32_e32 v55, v55
	v_pk_fma_f32 v[38:39], v[52:53], v[42:43], v[52:53] neg_lo:[1,0,0] neg_hi:[1,0,0]
	v_pk_mul_f32 v[52:53], v[62:63], v[62:63]
	v_pk_fma_f32 v[42:43], v[64:65], v[54:55], v[64:65] neg_lo:[1,0,0] neg_hi:[1,0,0]
	v_pk_mul_f32 v[54:55], v[50:51], v[50:51]
	v_pk_fma_f32 v[52:53], v[52:53], s[20:21], v[48:49] op_sel_hi:[1,0,0]
	v_pk_fma_f32 v[54:55], v[54:55], s[20:21], v[48:49] op_sel_hi:[1,0,0]
	v_pk_mul_f32 v[52:53], v[62:63], v[52:53]
	v_pk_mul_f32 v[54:55], v[50:51], v[54:55]
	v_exp_f32_e32 v52, v52
	v_exp_f32_e32 v53, v53
	v_exp_f32_e32 v54, v54
	v_exp_f32_e32 v55, v55
	v_pk_mul_f32 v[38:39], v[60:61], v[38:39]
	v_pk_add_f32 v[52:53], v[52:53], 1.0 op_sel_hi:[1,0]
	v_pk_mul_f32 v[42:43], v[56:57], v[42:43]
	v_pk_add_f32 v[54:55], v[54:55], 1.0 op_sel_hi:[1,0]
	v_rcp_f32_e32 v52, v52
	v_rcp_f32_e32 v53, v53
	v_rcp_f32_e32 v54, v54
	v_rcp_f32_e32 v55, v55
	v_cvt_pk_bf16_f32 v45, v38, v39
	v_pk_fma_f32 v[52:53], v[62:63], v[52:53], v[62:63] neg_lo:[1,0,0] neg_hi:[1,0,0]
	v_cvt_pk_bf16_f32 v41, v42, v43
	v_pk_fma_f32 v[50:51], v[50:51], v[54:55], v[50:51] neg_lo:[1,0,0] neg_hi:[1,0,0]
	v_pk_mul_f32 v[46:47], v[46:47], v[52:53]
	v_pk_mul_f32 v[34:35], v[34:35], v[50:51]
	ds_read2_b32 v[38:39], v225 offset0:32 offset1:36
	ds_read2_b32 v[42:43], v225 offset0:40 offset1:44
	v_cvt_pk_bf16_f32 v37, v46, v47
	v_cvt_pk_bf16_f32 v33, v34, v35
	ds_read2_b32 v[34:35], v225 offset0:96 offset1:100
	ds_read2_b32 v[46:47], v225 offset0:104 offset1:108
	s_waitcnt lgkmcnt(3)
;     __device__ __forceinline__ void operator()(const f32x4 (&acc)[2][2][4][2], const Unit& u, int wr, int wc, int fr, int fq) const {
;     ...
;             for (int n = 0; n < 2; ++n) {
;                 const f32x4 wg0 = wgt[n][0], wg1 = wgt[n][1], wg2 = wgt[n][2], bg = wgt[n][3], wv0 = wgt[n][4], wv1 = wgt[n][5], wv2 = wgt[n][6], bv = wgt[n][7];
; #pragma unroll
;                 for (int jp = 0; jp < 2; ++jp) {
;                     const int ja = 2 * jp, jb = 2 * jp + 1;
;                     const int vga = ((0 * 2 + n) * 4 + ja) * 2, vgb = ((0 * 2 + n) * 4 + jb) * 2, vva = ((1 * 2 + n) * 4 + ja) * 2, vvb = ((1 * 2 + n) * 4 + jb) * 2;
;                     const float hg2a = hl[vga * 4], hg1a = hl[(vga + 1) * 4], hg2b = hl[vgb * 4], hg1b = hl[(vgb + 1) * 4];
;                     const float hv2a = hl[vva * 4], hv1a = hl[(vva + 1) * 4], hv2b = hl[vvb * 4], hv1b = hl[(vvb + 1) * 4];
;     ...
;                     const f32x2 g0 = UC_PAIR(0, 0), g1 = UC_PAIR(0, 1), g2 = UC_PAIR(0, 2), g3 = UC_PAIR(0, 3);
;                     const f32x2 v0 = UC_PAIR(1, 0), v1 = UC_PAIR(1, 1), v2 = UC_PAIR(1, 2), v3 = UC_PAIR(1, 3);
;     ...
;                     f32x2 gp1, gp2, vp1, vp2;
;                     gp1.x = dpp_shr1_keep(hg1a, g3.x); gp1.y = dpp_shr1_keep(hg1b, g3.y); gp2.x = dpp_shr1_keep(hg2a, g2.x); gp2.y = dpp_shr1_keep(hg2b, g2.y);
;                     vp1.x = dpp_shr1_keep(hv1a, v3.x); vp1.y = dpp_shr1_keep(hv1b, v3.y); vp2.x = dpp_shr1_keep(hv2a, v2.x); vp2.y = dpp_shr1_keep(hv2b, v2.y);
;                     const f32x2 a0 = jp == 0 ? lo2(wg0) : hi2(wg0), a1 = jp == 0 ? lo2(wg1) : hi2(wg1), a2 = jp == 0 ? lo2(wg2) : hi2(wg2), ab = jp == 0 ? lo2(bg) : hi2(bg);
;                     const f32x2 c0 = jp == 0 ? lo2(wv0) : hi2(wv0), c1 = jp == 0 ? lo2(wv1) : hi2(wv1), c2 = jp == 0 ? lo2(wv2) : hi2(wv2), cb_ = jp == 0 ? lo2(bv) : hi2(bv);
;                     const f32x2 yg0 = ab + a0 * gp2 + a1 * gp1 + a2 * g0, yv0 = cb_ + c0 * vp2 + c1 * vp1 + c2 * v0;
;                     const f32x2 yg1 = ab + a0 * gp1 + a1 * g0 + a2 * g1, yv1 = cb_ + c0 * vp1 + c1 * v0 + c2 * v1;
;                     const f32x2 yg2 = ab + a0 * g0 + a1 * g1 + a2 * g2, yv2 = cb_ + c0 * v0 + c1 * v1 + c2 * v2;
;                     const f32x2 yg3 = ab + a0 * g1 + a1 * g2 + a2 * g3, yv3 = cb_ + c0 * v1 + c1 * v2 + c2 * v3;
	v_mov_b32_dpp v39, v16 row_shr:1 row_mask:0xf bank_mask:0xf
	s_waitcnt lgkmcnt(2)
	v_mov_b32_dpp v42, v21 row_shr:1 row_mask:0xf bank_mask:0xf
	v_mov_b32_dpp v43, v17 row_shr:1 row_mask:0xf bank_mask:0xf
	v_mov_b32_e32 v50, v39
	v_mov_b32_dpp v38, v20 row_shr:1 row_mask:0xf bank_mask:0xf
	v_mov_b32_e32 v39, v42
	s_waitcnt lgkmcnt(1)
	v_mov_b32_dpp v35, v0 row_shr:1 row_mask:0xf bank_mask:0xf
	s_waitcnt lgkmcnt(0)
	v_mov_b32_dpp v46, v5 row_shr:1 row_mask:0xf bank_mask:0xf
	v_mov_b32_e32 v51, v43
	v_mov_b32_dpp v47, v1 row_shr:1 row_mask:0xf bank_mask:0xf
	v_mov_b32_e32 v42, v35
	v_mov_b32_dpp v34, v4 row_shr:1 row_mask:0xf bank_mask:0xf
	v_mov_b32_e32 v35, v46
	v_pk_fma_f32 v[38:39], v[96:97], v[38:39], v[108:109]
	v_mov_b32_e32 v43, v47
	v_pk_fma_f32 v[38:39], v[100:101], v[50:51], v[38:39]
	v_pk_fma_f32 v[34:35], v[116:117], v[34:35], v[124:125]
	v_pk_fma_f32 v[46:47], v[96:97], v[50:51], v[108:109]
	v_pk_fma_f32 v[38:39], v[28:29], v[104:105], v[38:39]
	v_pk_fma_f32 v[34:35], v[120:121], v[42:43], v[34:35]
	v_pk_fma_f32 v[46:47], v[28:29], v[100:101], v[46:47]
	v_pk_fma_f32 v[42:43], v[116:117], v[42:43], v[124:125]
	v_pk_fma_f32 v[28:29], v[28:29], v[96:97], v[108:109]
	v_pk_fma_f32 v[34:35], v[12:13], v[112:113], v[34:35]
	v_pk_fma_f32 v[46:47], v[24:25], v[104:105], v[46:47]
	v_pk_fma_f32 v[42:43], v[12:13], v[120:121], v[42:43]
	v_pk_fma_f32 v[28:29], v[24:25], v[100:101], v[28:29]
	v_pk_fma_f32 v[12:13], v[12:13], v[116:117], v[124:125]
	v_pk_fma_f32 v[24:25], v[24:25], v[96:97], v[108:109]
	v_pk_fma_f32 v[42:43], v[8:9], v[112:113], v[42:43]
	v_pk_fma_f32 v[28:29], v[20:21], v[104:105], v[28:29]
	v_pk_fma_f32 v[12:13], v[8:9], v[120:121], v[12:13]
	v_pk_fma_f32 v[20:21], v[20:21], v[100:101], v[24:25]
	v_pk_fma_f32 v[8:9], v[8:9], v[116:117], v[124:125]
	v_pk_fma_f32 v[12:13], v[4:5], v[112:113], v[12:13]
	v_pk_fma_f32 v[16:17], v[16:17], v[104:105], v[20:21]
	v_pk_fma_f32 v[4:5], v[4:5], v[120:121], v[8:9]
	v_pk_mul_f32 v[8:9], v[38:39], v[38:39]
	v_pk_mul_f32 v[20:21], v[46:47], v[46:47]
	v_pk_fma_f32 v[8:9], v[8:9], s[20:21], v[48:49] op_sel_hi:[1,0,0]
	v_pk_fma_f32 v[20:21], v[20:21], s[20:21], v[48:49] op_sel_hi:[1,0,0]
	v_pk_mul_f32 v[8:9], v[38:39], v[8:9]
	v_pk_mul_f32 v[20:21], v[46:47], v[20:21]
	v_exp_f32_e32 v8, v8
	v_exp_f32_e32 v9, v9
	v_exp_f32_e32 v20, v20
	v_exp_f32_e32 v21, v21
	v_pk_fma_f32 v[0:1], v[0:1], v[112:113], v[4:5]
	v_pk_add_f32 v[8:9], v[8:9], 1.0 op_sel_hi:[1,0]
	v_pk_mul_f32 v[24:25], v[16:17], v[16:17]
	v_pk_add_f32 v[20:21], v[20:21], 1.0 op_sel_hi:[1,0]
	v_rcp_f32_e32 v8, v8
	v_rcp_f32_e32 v9, v9
	v_rcp_f32_e32 v20, v20
	v_rcp_f32_e32 v21, v21
	v_pk_fma_f32 v[24:25], v[24:25], s[20:21], v[48:49] op_sel_hi:[1,0,0]
	v_pk_fma_f32 v[4:5], v[38:39], v[8:9], v[38:39] neg_lo:[1,0,0] neg_hi:[1,0,0]
	v_pk_mul_f32 v[24:25], v[16:17], v[24:25]
	v_pk_fma_f32 v[8:9], v[46:47], v[20:21], v[46:47] neg_lo:[1,0,0] neg_hi:[1,0,0]
	v_pk_mul_f32 v[20:21], v[28:29], v[28:29]
	v_exp_f32_e32 v24, v24
	v_pk_fma_f32 v[20:21], v[20:21], s[20:21], v[48:49] op_sel_hi:[1,0,0]
	v_exp_f32_e32 v25, v25
	v_pk_mul_f32 v[20:21], v[28:29], v[20:21]
	v_pk_mul_f32 v[4:5], v[34:35], v[4:5]
	v_exp_f32_e32 v20, v20
	v_exp_f32_e32 v21, v21
	v_pk_add_f32 v[24:25], v[24:25], 1.0 op_sel_hi:[1,0]
	v_pk_mul_f32 v[8:9], v[42:43], v[8:9]
	v_rcp_f32_e32 v24, v24
	v_pk_add_f32 v[20:21], v[20:21], 1.0 op_sel_hi:[1,0]
	v_rcp_f32_e32 v25, v25
	v_rcp_f32_e32 v20, v20
	v_rcp_f32_e32 v21, v21
	v_cvt_pk_bf16_f32 v46, v4, v5
	v_pk_fma_f32 v[16:17], v[16:17], v[24:25], v[16:17] neg_lo:[1,0,0] neg_hi:[1,0,0]
	v_cvt_pk_bf16_f32 v42, v8, v9
	v_pk_fma_f32 v[20:21], v[28:29], v[20:21], v[28:29] neg_lo:[1,0,0] neg_hi:[1,0,0]
	v_pk_mul_f32 v[0:1], v[0:1], v[16:17]
	v_pk_mul_f32 v[12:13], v[12:13], v[20:21]
	ds_read2_b32 v[4:5], v225 offset0:48 offset1:52
	ds_read2_b32 v[8:9], v225 offset0:56 offset1:60
	v_cvt_pk_bf16_f32 v38, v12, v13
	v_cvt_pk_bf16_f32 v34, v0, v1
	ds_read2_b32 v[0:1], v225 offset0:112 offset1:116
	ds_read2_b32 v[12:13], v225 offset0:120 offset1:124
	s_waitcnt lgkmcnt(3)
	v_mov_b32_dpp v5, v18 row_shr:1 row_mask:0xf bank_mask:0xf
	s_waitcnt lgkmcnt(2)
	v_mov_b32_dpp v8, v23 row_shr:1 row_mask:0xf bank_mask:0xf
	v_mov_b32_dpp v9, v19 row_shr:1 row_mask:0xf bank_mask:0xf
	s_waitcnt lgkmcnt(1)
; __device__ __forceinline__ unsigned cvt_pk_bf16(float lo, float hi) { unsigned r; asm("v_cvt_pk_bf16_f32 %0, %1, %2" : "=v"(r) : "v"(lo), "v"(hi)); return r; }
;     __device__ __forceinline__ void operator()(const f32x4 (&acc)[2][2][4][2], const Unit& u, int wr, int wc, int fr, int fq) const {
;     ...
;                     gp1.x = dpp_shr1_keep(hg1a, g3.x); gp1.y = dpp_shr1_keep(hg1b, g3.y); gp2.x = dpp_shr1_keep(hg2a, g2.x); gp2.y = dpp_shr1_keep(hg2b, g2.y);
;                     vp1.x = dpp_shr1_keep(hv1a, v3.x); vp1.y = dpp_shr1_keep(hv1b, v3.y); vp2.x = dpp_shr1_keep(hv2a, v2.x); vp2.y = dpp_shr1_keep(hv2b, v2.y);
;                     const f32x2 a0 = jp == 0 ? lo2(wg0) : hi2(wg0), a1 = jp == 0 ? lo2(wg1) : hi2(wg1), a2 = jp == 0 ? lo2(wg2) : hi2(wg2), ab = jp == 0 ? lo2(bg) : hi2(bg);
;                     const f32x2 c0 = jp == 0 ? lo2(wv0) : hi2(wv0), c1 = jp == 0 ? lo2(wv1) : hi2(wv1), c2 = jp == 0 ? lo2(wv2) : hi2(wv2), cb_ = jp == 0 ? lo2(bv) : hi2(bv);
;                     const f32x2 yg0 = ab + a0 * gp2 + a1 * gp1 + a2 * g0, yv0 = cb_ + c0 * vp2 + c1 * vp1 + c2 * v0;
;                     const f32x2 yg1 = ab + a0 * gp1 + a1 * g0 + a2 * g1, yv1 = cb_ + c0 * vp1 + c1 * v0 + c2 * v1;
;                     const f32x2 yg2 = ab + a0 * g0 + a1 * g1 + a2 * g2, yv2 = cb_ + c0 * v0 + c1 * v1 + c2 * v2;
;                     const f32x2 yg3 = ab + a0 * g1 + a1 * g2 + a2 * g3, yv3 = cb_ + c0 * v1 + c1 * v2 + c2 * v3;
;                     const f32x2 r0 = gelu_tanh_fast2(yg0) * yv0, r1 = gelu_tanh_fast2(yg1) * yv1, r2 = gelu_tanh_fast2(yg2) * yv2, r3 = gelu_tanh_fast2(yg3) * yv3;
;                     const unsigned q0 = cvt_pk_bf16(r0.x, r0.y), q1 = cvt_pk_bf16(r1.x, r1.y), q2 = cvt_pk_bf16(r2.x, r2.y), q3 = cvt_pk_bf16(r3.x, r3.y);
;                     if (jp == 0) { pk[0][n].x = q0; pk[1][n].x = q1; pk[2][n].x = q2; pk[3][n].x = q3; } else { pk[0][n].y = q0; pk[1][n].y = q1; pk[2][n].y = q2; pk[3][n].y = q3; }
;                 }
;             }
;             bf16_t* op = ACT + (size_t)(tok0 + ai * HALF) * DFF + ch0;
;             const bool top = (ai == 0) && (wr == 0) && (fr == 0);
; #pragma unroll
;             for (int m = 0; m < 4; ++m) { const u32x4 w = (u32x4){pk[m][0].x, pk[m][0].y, pk[m][1].x, pk[m][1].y};
;                 if (!(top && m < 2)) *(u32x4*)(op + (size_t)m * DFF) = w; }
	v_mov_b32_dpp v1, v2 row_shr:1 row_mask:0xf bank_mask:0xf
	s_waitcnt lgkmcnt(0)
	v_mov_b32_dpp v12, v7 row_shr:1 row_mask:0xf bank_mask:0xf
	v_mov_b32_e32 v16, v5
	v_mov_b32_e32 v5, v8
	v_mov_b32_dpp v13, v3 row_shr:1 row_mask:0xf bank_mask:0xf
	v_mov_b32_e32 v8, v1
	v_mov_b32_dpp v0, v6 row_shr:1 row_mask:0xf bank_mask:0xf
	v_mov_b32_e32 v1, v12
	v_mov_b32_e32 v17, v9
	v_mov_b32_dpp v4, v22 row_shr:1 row_mask:0xf bank_mask:0xf
	v_mov_b32_e32 v9, v13
	v_pk_fma_f32 v[0:1], v[118:119], v[0:1], v[126:127]
	v_pk_fma_f32 v[4:5], v[98:99], v[4:5], v[110:111]
	v_pk_fma_f32 v[0:1], v[122:123], v[8:9], v[0:1]
	v_pk_fma_f32 v[8:9], v[118:119], v[8:9], v[126:127]
	v_pk_fma_f32 v[4:5], v[102:103], v[16:17], v[4:5]
	v_pk_fma_f32 v[0:1], v[14:15], v[114:115], v[0:1]
	v_pk_fma_f32 v[8:9], v[14:15], v[122:123], v[8:9]
	v_pk_fma_f32 v[14:15], v[14:15], v[118:119], v[126:127]
	v_pk_fma_f32 v[4:5], v[30:31], v[106:107], v[4:5]
	v_pk_fma_f32 v[8:9], v[10:11], v[114:115], v[8:9]
	v_pk_fma_f32 v[14:15], v[10:11], v[122:123], v[14:15]
	v_pk_fma_f32 v[10:11], v[10:11], v[118:119], v[126:127]
	v_pk_fma_f32 v[14:15], v[6:7], v[114:115], v[14:15]
	v_pk_fma_f32 v[6:7], v[6:7], v[122:123], v[10:11]
	v_pk_mul_f32 v[10:11], v[4:5], v[4:5]
	v_pk_fma_f32 v[12:13], v[98:99], v[16:17], v[110:111]
	v_pk_fma_f32 v[10:11], v[10:11], s[20:21], v[48:49] op_sel_hi:[1,0,0]
	v_pk_fma_f32 v[12:13], v[30:31], v[102:103], v[12:13]
	v_pk_mul_f32 v[10:11], v[4:5], v[10:11]
	v_pk_fma_f32 v[20:21], v[26:27], v[98:99], v[110:111]
	v_exp_f32_e32 v10, v10
	v_exp_f32_e32 v11, v11
	v_pk_fma_f32 v[12:13], v[26:27], v[106:107], v[12:13]
	v_pk_fma_f32 v[20:21], v[22:23], v[102:103], v[20:21]
	v_pk_fma_f32 v[16:17], v[30:31], v[98:99], v[110:111]
	v_pk_add_f32 v[10:11], v[10:11], 1.0 op_sel_hi:[1,0]
	v_pk_fma_f32 v[18:19], v[18:19], v[106:107], v[20:21]
	v_rcp_f32_e32 v10, v10
	v_rcp_f32_e32 v11, v11
	v_pk_mul_f32 v[20:21], v[12:13], v[12:13]
	v_pk_fma_f32 v[16:17], v[26:27], v[102:103], v[16:17]
	v_pk_fma_f32 v[20:21], v[20:21], s[20:21], v[48:49] op_sel_hi:[1,0,0]
	v_pk_fma_f32 v[4:5], v[4:5], v[10:11], v[4:5] neg_lo:[1,0,0] neg_hi:[1,0,0]
	v_pk_mul_f32 v[10:11], v[18:19], v[18:19]
	v_pk_mul_f32 v[20:21], v[12:13], v[20:21]
	v_pk_fma_f32 v[10:11], v[10:11], s[20:21], v[48:49] op_sel_hi:[1,0,0]
	v_exp_f32_e32 v20, v20
	v_exp_f32_e32 v21, v21
	v_pk_mul_f32 v[10:11], v[18:19], v[10:11]
	v_pk_fma_f32 v[16:17], v[22:23], v[106:107], v[16:17]
	v_exp_f32_e32 v10, v10
	v_exp_f32_e32 v11, v11
	v_pk_add_f32 v[20:21], v[20:21], 1.0 op_sel_hi:[1,0]
	v_pk_fma_f32 v[2:3], v[2:3], v[114:115], v[6:7]
	v_rcp_f32_e32 v20, v20
	v_rcp_f32_e32 v21, v21
	v_pk_add_f32 v[10:11], v[10:11], 1.0 op_sel_hi:[1,0]
	v_pk_mul_f32 v[0:1], v[0:1], v[4:5]
	v_rcp_f32_e32 v10, v10
	v_rcp_f32_e32 v11, v11
	v_pk_fma_f32 v[4:5], v[12:13], v[20:21], v[12:13] neg_lo:[1,0,0] neg_hi:[1,0,0]
	v_pk_mul_f32 v[6:7], v[16:17], v[16:17]
	v_pk_mul_f32 v[4:5], v[8:9], v[4:5]
	v_pk_fma_f32 v[6:7], v[6:7], s[20:21], v[48:49] op_sel_hi:[1,0,0]
	v_pk_fma_f32 v[8:9], v[18:19], v[10:11], v[18:19] neg_lo:[1,0,0] neg_hi:[1,0,0]
	v_pk_mul_f32 v[6:7], v[16:17], v[6:7]
	v_pk_mul_f32 v[2:3], v[2:3], v[8:9]
	v_exp_f32_e32 v6, v6
	v_exp_f32_e32 v7, v7
	v_cvt_pk_bf16_f32 v47, v0, v1
	v_cvt_pk_bf16_f32 v35, v2, v3
	v_add_u32_e32 v2, 0x80, v226
	v_mov_b64_e32 v[0:1], s[82:83]
	v_mad_i64_i32 v[0:1], s[20:21], v2, s73, v[0:1]
	v_lshl_add_u64 v[0:1], v[220:221], 1, v[0:1]
	v_add_co_u32_e32 v2, vcc, 0x2000, v0
	v_pk_add_f32 v[6:7], v[6:7], 1.0 op_sel_hi:[1,0]
	s_nop 0
	v_addc_co_u32_e32 v3, vcc, 0, v1, vcc
	v_rcp_f32_e32 v6, v6
	v_rcp_f32_e32 v7, v7
	v_cvt_pk_bf16_f32 v43, v4, v5
	global_store_dwordx4 v[2:3], v[40:43], off offset:3072 sc1
	v_add_co_u32_e32 v2, vcc, 0x5000, v0
	global_store_dwordx4 v[0:1], v[44:47], off sc1
	s_nop 0
	v_addc_co_u32_e32 v3, vcc, 0, v1, vcc
	v_add_co_u32_e32 v0, vcc, 0x8000, v0
	v_pk_fma_f32 v[6:7], v[16:17], v[6:7], v[16:17] neg_lo:[1,0,0] neg_hi:[1,0,0]
	s_nop 0
	v_addc_co_u32_e32 v1, vcc, 0, v1, vcc
	s_andn2_b64 vcc, exec, s[46:47]
	s_mov_b64 s[20:21], -1
	v_pk_mul_f32 v[6:7], v[14:15], v[6:7]
	global_store_dwordx4 v[0:1], v[32:35], off offset:1024 sc1
	v_cvt_pk_bf16_f32 v39, v6, v7
	global_store_dwordx4 v[2:3], v[36:39], off offset:2048 sc1
	s_cbranch_vccnz .LBB0_524
	s_andn2_b64 vcc, exec, s[0:1]
	s_cbranch_vccnz .LBB0_523
	s_barrier
	s_branch .LBB0_523
